# item loop: next item's descriptor / query-id LDS reads issued at commit (in flight under the score MFMAs) instead of at the loop top
# baseline (speedup 1.0000x reference)
.Lit_top:
	v_cndmask_b32_e64 v140, v141, v139, s[14:15]
	s_waitcnt lgkmcnt(0)
	v_readfirstlane_b32 s55, v133
	v_cmp_ne_u16_sdwa s[58:59], v135, s79 src0_sel:BYTE_0 src1_sel:DWORD
	s_and_b32 s4, s55, 0xff
	s_cmp_eq_u32 s4, s54
	s_cselect_b64 s[56:57], -1, 0
	v_cndmask_b32_e64 v135, 0, v135, s[58:59]
	v_and_b32_e32 v136, 63, v135
	v_lshl_or_b32 v130, v136, 2, v227
	v_mad_u32_u24 v137, v130, s66, v188
	ds_read_b128 v[114:117], v137
	ds_read_b128 v[118:121], v137 offset:32
	ds_read_b128 v[122:125], v137 offset:64
	ds_read_b128 v[126:129], v137 offset:96
	v_lshlrev_b32_e32 v138, 2, v130
	v_add_u32_e32 v138, 0x10d00, v138
	ds_read_b32 v139, v138
	s_and_b64 vcc, exec, s[16:17]
	s_cbranch_vccnz .Lit_far
	s_sub_i32 s4, s44, s22
	v_lshl_add_u32 v34, s4, 6, v46
	s_nop 0
	v_sub_u32_e32 v34, v34, v181
	v_add_u32_e32 v36, -1, v34
	v_add_u32_e32 v38, -2, v34
	v_add_u32_e32 v40, -3, v34
	v_add_u32_e32 v42, -8, v34
	v_add_u32_e32 v44, -9, v34
	v_add_u32_e32 v46, -10, v34
	v_add_u32_e32 v48, -11, v34
	v_med3_i32 v35, v34, 0, v220
	v_med3_i32 v37, v36, 0, v220
	v_med3_i32 v39, v38, 0, v220
	v_med3_i32 v41, v40, 0, v220
	v_med3_i32 v43, v42, 0, v220
	v_med3_i32 v45, v44, 0, v220
	v_med3_i32 v47, v46, 0, v220
	v_med3_i32 v49, v48, 0, v220
	v_lshl_add_u32 v35, v35, 2, v180
	v_lshl_add_u32 v37, v37, 2, v180
	v_lshl_add_u32 v39, v39, 2, v180
	v_lshl_add_u32 v41, v41, 2, v180
	v_lshl_add_u32 v43, v43, 2, v180
	v_lshl_add_u32 v45, v45, 2, v180
	v_lshl_add_u32 v47, v47, 2, v180
	v_lshl_add_u32 v49, v49, 2, v180
	ds_read_b32 v35, v35
	ds_read_b32 v37, v37
	ds_read_b32 v39, v39
	ds_read_b32 v41, v41
	ds_read_b32 v43, v43
	ds_read_b32 v45, v45
	ds_read_b32 v47, v47
	ds_read_b32 v49, v49
	s_waitcnt lgkmcnt(7)
	v_add_f32_e32 v18, v18, v35
	v_cmp_lt_i32_e32 vcc, -1, v34
	v_mul_f32_e32 v18, 0x3fb8aa3b, v18
	s_and_b64 vcc, s[14:15], vcc
	v_cndmask_b32_e32 v18, v219, v18, vcc
	s_waitcnt lgkmcnt(6)
	v_add_f32_e32 v19, v19, v37
	v_cmp_lt_i32_e32 vcc, -1, v36
	v_mul_f32_e32 v19, 0x3fb8aa3b, v19
	s_and_b64 vcc, s[14:15], vcc
	v_cndmask_b32_e32 v19, v219, v19, vcc
	s_waitcnt lgkmcnt(5)
	v_add_f32_e32 v20, v20, v39
	v_cmp_lt_i32_e32 vcc, -1, v38
	v_mul_f32_e32 v20, 0x3fb8aa3b, v20
	s_and_b64 vcc, s[14:15], vcc
	v_cndmask_b32_e32 v20, v219, v20, vcc
	s_waitcnt lgkmcnt(4)
	v_add_f32_e32 v21, v21, v41
	v_cmp_lt_i32_e32 vcc, -1, v40
	v_mul_f32_e32 v21, 0x3fb8aa3b, v21
	s_and_b64 vcc, s[14:15], vcc
	v_cndmask_b32_e32 v21, v219, v21, vcc
	s_waitcnt lgkmcnt(3)
	v_add_f32_e32 v22, v22, v43
	v_cmp_lt_i32_e32 vcc, -1, v42
	v_mul_f32_e32 v22, 0x3fb8aa3b, v22
	s_and_b64 vcc, s[14:15], vcc
	v_cndmask_b32_e32 v22, v219, v22, vcc
	s_waitcnt lgkmcnt(2)
	v_add_f32_e32 v23, v23, v45
	v_cmp_lt_i32_e32 vcc, -1, v44
	v_mul_f32_e32 v23, 0x3fb8aa3b, v23
	s_and_b64 vcc, s[14:15], vcc
	v_cndmask_b32_e32 v23, v219, v23, vcc
	s_waitcnt lgkmcnt(1)
	v_add_f32_e32 v24, v24, v47
	v_cmp_lt_i32_e32 vcc, -1, v46
	v_mul_f32_e32 v24, 0x3fb8aa3b, v24
	s_and_b64 vcc, s[14:15], vcc
	s_waitcnt lgkmcnt(0)
	v_add_f32_e32 v25, v25, v49
	v_add_u32_e32 v35, -16, v34
	v_subrev_u32_e32 v37, 17, v34
	v_subrev_u32_e32 v39, 18, v34
	v_subrev_u32_e32 v41, 19, v34
	v_subrev_u32_e32 v43, 24, v34
	v_subrev_u32_e32 v45, 25, v34
	v_subrev_u32_e32 v47, 26, v34
	v_subrev_u32_e32 v49, 27, v34
	v_cndmask_b32_e32 v24, v219, v24, vcc
	v_cmp_lt_i32_e32 vcc, -1, v48
	v_med3_i32 v36, v35, 0, v220
	v_med3_i32 v38, v37, 0, v220
	v_med3_i32 v40, v39, 0, v220
	v_med3_i32 v42, v41, 0, v220
	v_med3_i32 v44, v43, 0, v220
	v_med3_i32 v46, v45, 0, v220
	v_med3_i32 v48, v47, 0, v220
	v_med3_i32 v190, v49, 0, v220
	v_mul_f32_e32 v25, 0x3fb8aa3b, v25
	s_and_b64 vcc, s[14:15], vcc
	v_lshl_add_u32 v36, v36, 2, v180
	v_lshl_add_u32 v38, v38, 2, v180
	v_lshl_add_u32 v40, v40, 2, v180
	v_lshl_add_u32 v42, v42, 2, v180
	v_lshl_add_u32 v44, v44, 2, v180
	v_lshl_add_u32 v46, v46, 2, v180
	v_lshl_add_u32 v48, v48, 2, v180
	v_lshl_add_u32 v190, v190, 2, v180
	v_cndmask_b32_e32 v25, v219, v25, vcc
	ds_read_b32 v36, v36
	ds_read_b32 v38, v38
	ds_read_b32 v40, v40
	ds_read_b32 v42, v42
	ds_read_b32 v44, v44
	ds_read_b32 v46, v46
	ds_read_b32 v48, v48
	ds_read_b32 v190, v190
	s_waitcnt lgkmcnt(7)
	v_add_f32_e32 v26, v26, v36
	v_cmp_lt_i32_e32 vcc, -1, v35
	v_mul_f32_e32 v26, 0x3fb8aa3b, v26
	s_and_b64 vcc, s[14:15], vcc
	v_cndmask_b32_e32 v26, v219, v26, vcc
	s_waitcnt lgkmcnt(6)
	v_add_f32_e32 v27, v27, v38
	v_cmp_lt_i32_e32 vcc, -1, v37
	v_mul_f32_e32 v27, 0x3fb8aa3b, v27
	s_and_b64 vcc, s[14:15], vcc
	v_cndmask_b32_e32 v27, v219, v27, vcc
	s_waitcnt lgkmcnt(5)
	v_add_f32_e32 v28, v28, v40
	v_cmp_lt_i32_e32 vcc, -1, v39
	v_mul_f32_e32 v28, 0x3fb8aa3b, v28
	s_and_b64 vcc, s[14:15], vcc
	v_cndmask_b32_e32 v28, v219, v28, vcc
	s_waitcnt lgkmcnt(4)
	v_add_f32_e32 v29, v29, v42
	v_cmp_lt_i32_e32 vcc, -1, v41
	v_mul_f32_e32 v29, 0x3fb8aa3b, v29
	s_and_b64 vcc, s[14:15], vcc
	v_cndmask_b32_e32 v29, v219, v29, vcc
	s_waitcnt lgkmcnt(3)
	v_add_f32_e32 v30, v30, v44
	v_cmp_lt_i32_e32 vcc, -1, v43
	v_mul_f32_e32 v30, 0x3fb8aa3b, v30
	s_and_b64 vcc, s[14:15], vcc
	v_cndmask_b32_e32 v30, v219, v30, vcc
	s_waitcnt lgkmcnt(2)
	v_add_f32_e32 v31, v31, v46
	v_cmp_lt_i32_e32 vcc, -1, v45
	v_mul_f32_e32 v31, 0x3fb8aa3b, v31
	s_and_b64 vcc, s[14:15], vcc
	v_cndmask_b32_e32 v31, v219, v31, vcc
	s_waitcnt lgkmcnt(1)
	v_add_f32_e32 v32, v32, v48
	v_cmp_lt_i32_e32 vcc, -1, v47
	v_mul_f32_e32 v32, 0x3fb8aa3b, v32
	s_and_b64 vcc, s[14:15], vcc
	v_cndmask_b32_e32 v32, v219, v32, vcc
	v_cmp_lt_i32_e32 vcc, -1, v49
	v_subrev_u32_e32 v35, 32, v34
	v_subrev_u32_e32 v37, 33, v34
	v_subrev_u32_e32 v39, 34, v34
	v_subrev_u32_e32 v41, 35, v34
	v_subrev_u32_e32 v43, 40, v34
	v_subrev_u32_e32 v45, 41, v34
	v_subrev_u32_e32 v47, 42, v34
	v_subrev_u32_e32 v49, 43, v34
	s_waitcnt lgkmcnt(0)
	v_add_f32_e32 v33, v33, v190
	v_med3_i32 v36, v35, 0, v220
	v_med3_i32 v38, v37, 0, v220
	v_med3_i32 v40, v39, 0, v220
	v_med3_i32 v42, v41, 0, v220
	v_med3_i32 v44, v43, 0, v220
	v_med3_i32 v46, v45, 0, v220
	v_med3_i32 v48, v47, 0, v220
	v_med3_i32 v190, v49, 0, v220
	v_mul_f32_e32 v33, 0x3fb8aa3b, v33
	s_and_b64 vcc, s[14:15], vcc
	v_lshl_add_u32 v36, v36, 2, v180
	v_lshl_add_u32 v38, v38, 2, v180
	v_lshl_add_u32 v40, v40, 2, v180
	v_lshl_add_u32 v42, v42, 2, v180
	v_lshl_add_u32 v44, v44, 2, v180
	v_lshl_add_u32 v46, v46, 2, v180
	v_lshl_add_u32 v48, v48, 2, v180
	v_lshl_add_u32 v190, v190, 2, v180
	v_cndmask_b32_e32 v33, v219, v33, vcc
	ds_read_b32 v36, v36
	ds_read_b32 v38, v38
	ds_read_b32 v40, v40
	ds_read_b32 v42, v42
	ds_read_b32 v44, v44
	ds_read_b32 v46, v46
	ds_read_b32 v48, v48
	ds_read_b32 v190, v190
	s_waitcnt lgkmcnt(7)
	v_add_f32_e32 v2, v2, v36
	v_cmp_lt_i32_e32 vcc, -1, v35
	v_mul_f32_e32 v2, 0x3fb8aa3b, v2
	s_and_b64 vcc, s[14:15], vcc
	v_cndmask_b32_e32 v2, v219, v2, vcc
	s_waitcnt lgkmcnt(6)
	v_add_f32_e32 v3, v3, v38
	v_cmp_lt_i32_e32 vcc, -1, v37
	v_mul_f32_e32 v3, 0x3fb8aa3b, v3
	s_and_b64 vcc, s[14:15], vcc
	v_cndmask_b32_e32 v3, v219, v3, vcc
	s_waitcnt lgkmcnt(5)
	v_add_f32_e32 v4, v4, v40
	v_cmp_lt_i32_e32 vcc, -1, v39
	v_mul_f32_e32 v4, 0x3fb8aa3b, v4
	s_and_b64 vcc, s[14:15], vcc
	v_cndmask_b32_e32 v4, v219, v4, vcc
	s_waitcnt lgkmcnt(4)
	v_add_f32_e32 v5, v5, v42
	v_cmp_lt_i32_e32 vcc, -1, v41
	v_mul_f32_e32 v5, 0x3fb8aa3b, v5
	s_and_b64 vcc, s[14:15], vcc
	v_cndmask_b32_e32 v5, v219, v5, vcc
	s_waitcnt lgkmcnt(3)
	v_add_f32_e32 v6, v6, v44
	v_cmp_lt_i32_e32 vcc, -1, v43
	v_mul_f32_e32 v6, 0x3fb8aa3b, v6
	s_and_b64 vcc, s[14:15], vcc
	v_cndmask_b32_e32 v6, v219, v6, vcc
	s_waitcnt lgkmcnt(2)
	v_add_f32_e32 v7, v7, v46
	v_cmp_lt_i32_e32 vcc, -1, v45
	v_mul_f32_e32 v7, 0x3fb8aa3b, v7
	s_and_b64 vcc, s[14:15], vcc
	v_cndmask_b32_e32 v7, v219, v7, vcc
	s_waitcnt lgkmcnt(1)
	v_add_f32_e32 v8, v8, v48
	v_cmp_lt_i32_e32 vcc, -1, v47
	v_mul_f32_e32 v8, 0x3fb8aa3b, v8
	s_and_b64 vcc, s[14:15], vcc
	v_subrev_u32_e32 v35, 48, v34
	v_subrev_u32_e32 v37, 49, v34
	v_subrev_u32_e32 v39, 50, v34
	v_subrev_u32_e32 v41, 51, v34
	v_subrev_u32_e32 v43, 56, v34
	v_subrev_u32_e32 v45, 57, v34
	v_subrev_u32_e32 v47, 58, v34
	v_subrev_u32_e32 v34, 59, v34
	v_cndmask_b32_e32 v8, v219, v8, vcc
	s_waitcnt lgkmcnt(0)
	v_add_f32_e32 v9, v9, v190
	v_cmp_lt_i32_e32 vcc, -1, v49
	v_med3_i32 v36, v35, 0, v220
	v_med3_i32 v38, v37, 0, v220
	v_med3_i32 v40, v39, 0, v220
	v_med3_i32 v42, v41, 0, v220
	v_med3_i32 v44, v43, 0, v220
	v_med3_i32 v46, v45, 0, v220
	v_med3_i32 v48, v47, 0, v220
	v_med3_i32 v49, v34, 0, v220
	v_mul_f32_e32 v9, 0x3fb8aa3b, v9
	s_and_b64 vcc, s[14:15], vcc
	v_lshl_add_u32 v36, v36, 2, v180
	v_lshl_add_u32 v38, v38, 2, v180
	v_lshl_add_u32 v40, v40, 2, v180
	v_lshl_add_u32 v42, v42, 2, v180
	v_lshl_add_u32 v44, v44, 2, v180
	v_lshl_add_u32 v46, v46, 2, v180
	v_lshl_add_u32 v48, v48, 2, v180
	v_lshl_add_u32 v49, v49, 2, v180
	v_cndmask_b32_e32 v9, v219, v9, vcc
	ds_read_b32 v36, v36
	ds_read_b32 v38, v38
	ds_read_b32 v40, v40
	ds_read_b32 v42, v42
	ds_read_b32 v44, v44
	ds_read_b32 v46, v46
	ds_read_b32 v48, v48
	ds_read_b32 v49, v49
	s_waitcnt lgkmcnt(7)
	v_add_f32_e32 v10, v10, v36
	v_cmp_lt_i32_e32 vcc, -1, v35
	v_mul_f32_e32 v10, 0x3fb8aa3b, v10
	s_and_b64 vcc, s[14:15], vcc
	v_cndmask_b32_e32 v10, v219, v10, vcc
	s_waitcnt lgkmcnt(6)
	v_add_f32_e32 v11, v11, v38
	v_cmp_lt_i32_e32 vcc, -1, v37
	v_mul_f32_e32 v11, 0x3fb8aa3b, v11
	s_and_b64 vcc, s[14:15], vcc
	v_cndmask_b32_e32 v11, v219, v11, vcc
	s_waitcnt lgkmcnt(5)
	v_add_f32_e32 v12, v12, v40
	v_cmp_lt_i32_e32 vcc, -1, v39
	v_mul_f32_e32 v12, 0x3fb8aa3b, v12
	s_and_b64 vcc, s[14:15], vcc
	v_cndmask_b32_e32 v12, v219, v12, vcc
	s_waitcnt lgkmcnt(4)
	v_add_f32_e32 v13, v13, v42
	v_cmp_lt_i32_e32 vcc, -1, v41
	v_mul_f32_e32 v13, 0x3fb8aa3b, v13
	s_and_b64 vcc, s[14:15], vcc
	v_cndmask_b32_e32 v13, v219, v13, vcc
	s_waitcnt lgkmcnt(3)
	v_add_f32_e32 v14, v14, v44
	v_cmp_lt_i32_e32 vcc, -1, v43
	v_mul_f32_e32 v14, 0x3fb8aa3b, v14
	s_and_b64 vcc, s[14:15], vcc
	v_cndmask_b32_e32 v14, v219, v14, vcc
	s_waitcnt lgkmcnt(2)
	v_add_f32_e32 v15, v15, v46
	v_cmp_lt_i32_e32 vcc, -1, v45
	v_mul_f32_e32 v15, 0x3fb8aa3b, v15
	s_and_b64 vcc, s[14:15], vcc
	v_cndmask_b32_e32 v15, v219, v15, vcc
	s_waitcnt lgkmcnt(1)
	v_add_f32_e32 v16, v16, v48
	v_cmp_lt_i32_e32 vcc, -1, v47
	v_mul_f32_e32 v16, 0x3fb8aa3b, v16
	s_and_b64 vcc, s[14:15], vcc
	v_cndmask_b32_e32 v16, v219, v16, vcc
	s_waitcnt lgkmcnt(0)
	v_add_f32_e32 v17, v17, v49
	v_cmp_lt_i32_e32 vcc, -1, v34
	v_mul_f32_e32 v17, 0x3fb8aa3b, v17
	s_and_b64 vcc, s[14:15], vcc
	v_cndmask_b32_e32 v17, v219, v17, vcc

.Lit_nov:
.Lit_commit:
	s_add_i32 s53, s53, 1
	s_mov_b32 s22, s54
	s_mov_b32 s26, s55
	s_mov_b64 s[12:13], s[56:57]
	s_mov_b64 s[14:15], s[58:59]
	v_mov_b32_e32 v189, v130
	v_mov_b32_e32 v46, v136
	s_cmp_lt_i32 s22, s96
	s_cselect_b64 s[16:17], -1, 0
	s_and_b64 s[60:61], s[8:9], s[14:15]
	s_mov_b32 s24, 0
	v_mov_b32_e32 v132, s99
	ds_read_b32 v133, v132
	ds_read_u8 v135, v134
	s_and_b32 s54, s26, 0xff
	s_add_i32 s99, s99, 4
	v_add_u32_e32 v134, 8, v134
	s_waitcnt vmcnt(8) lgkmcnt(15)
	v_mfma_f32_32x32x16_bf16 v[18:33], v[50:53], v[114:117], 0
	v_mfma_f32_32x32x16_bf16 v[2:17], v[66:69], v[114:117], 0
	v_mfma_f32_32x32x16_bf16 v[18:33], v[54:57], v[118:121], v[18:33]
	v_mfma_f32_32x32x16_bf16 v[2:17], v[78:81], v[118:121], v[2:17]
	v_mfma_f32_32x32x16_bf16 v[18:33], v[58:61], v[122:125], v[18:33]
	v_mfma_f32_32x32x16_bf16 v[2:17], v[90:93], v[122:125], v[2:17]
	v_mfma_f32_32x32x16_bf16 v[18:33], v[62:65], v[126:129], v[18:33]
	v_mfma_f32_32x32x16_bf16 v[2:17], v[98:101], v[126:129], v[2:17]
	s_and_b64 vcc, exec, s[12:13]
	s_cbranch_vccnz .Lit_top
	s_add_i32 s4, s53, 1
	s_cmp_ge_u32 s4, s32
	s_cbranch_scc1 .Lit_top
	s_mov_b32 s24, 1
	s_and_b32 s4, s26, 0xff
	s_lshl_b32 s4, s4, 13
	s_add_u32 s4, s48, s4
	s_addc_u32 s5, s49, 0
	global_load_dwordx4 v[50:53], v194, s[4:5]
	global_load_dwordx4 v[54:57], v194, s[4:5] offset:1024
	global_load_dwordx4 v[58:61], v194, s[4:5] offset:2048
	global_load_dwordx4 v[62:65], v194, s[4:5] offset:3072
	global_load_dwordx4 v[66:69], v200, s[4:5]
	global_load_dwordx4 v[78:81], v202, s[4:5]
	global_load_dwordx4 v[90:93], v204, s[4:5]
	global_load_dwordx4 v[98:101], v206, s[4:5]
	s_branch .Lit_top
